# grid-barrier spin loops poll without the s_sleep between polls; on top of v76
# speedup vs baseline: 1.0069x; 1.0069x over previous
.LBB0_19:
	v_readlane_b32 s2, v249, 10
	v_readlane_b32 s3, v249, 11
	global_load_dword v12, v1, s[26:27] offset:1024 sc1
	global_load_dword v0, v1, s[26:27] offset:1280 sc1
	s_waitcnt lgkmcnt(0)
	global_load_dword v2, v1, s[26:27] offset:1536 sc1
	global_load_dword v3, v1, s[26:27] offset:1792 sc1
	global_load_dword v4, v1, s[26:27] offset:2048 sc1
	global_load_dword v5, v1, s[26:27] offset:2304 sc1
	global_load_dword v6, v1, s[26:27] offset:2560 sc1
	global_load_dword v7, v1, s[26:27] offset:2816 sc1
	global_load_dword v8, v1, s[26:27] offset:3072 sc1
	global_load_dword v9, v1, s[26:27] offset:3328 sc1
	global_load_dword v10, v1, s[26:27] offset:3584 sc1
	global_load_dword v11, v1, s[26:27] offset:3840 sc1
	global_load_dword v13, v1, s[2:3] sc1
	v_readlane_b32 s2, v249, 12
	v_readlane_b32 s3, v249, 13
	s_mov_b64 s[28:29], -1
	s_waitcnt vmcnt(11)
	v_add_u32_e32 v17, v0, v12
	s_nop 1
	global_load_dword v14, v1, s[2:3] sc1
	v_readlane_b32 s2, v249, 14
	v_readlane_b32 s3, v249, 15
	s_waitcnt vmcnt(11)
	v_add_u32_e32 v17, v17, v2
	s_waitcnt vmcnt(10)
	v_add_u32_e32 v17, v17, v3
	s_waitcnt vmcnt(9)
	v_add_u32_e32 v17, v17, v4
	s_waitcnt vmcnt(8)
	v_add_u32_e32 v17, v17, v5
	s_waitcnt vmcnt(7)
	v_add_u32_e32 v17, v17, v6
	global_load_dword v15, v1, s[2:3] sc1
	v_readlane_b32 s2, v249, 16
	v_readlane_b32 s3, v249, 17
	s_waitcnt vmcnt(7)
	v_add_u32_e32 v17, v17, v7
	s_waitcnt vmcnt(6)
	v_add_u32_e32 v17, v17, v8
	s_waitcnt vmcnt(5)
	v_add_u32_e32 v17, v17, v9
	s_waitcnt vmcnt(4)
	v_add_u32_e32 v17, v17, v10
	s_waitcnt vmcnt(3)
	v_add_u32_e32 v17, v17, v11
	global_load_dword v16, v1, s[2:3] sc1
	s_waitcnt vmcnt(3)
	v_add_u32_e32 v17, v17, v13
	s_mov_b64 s[2:3], -1
	s_waitcnt vmcnt(2)
	v_add_u32_e32 v17, v17, v14
	s_waitcnt vmcnt(1)
	v_add_u32_e32 v17, v17, v15
	s_waitcnt vmcnt(0)
	v_add_u32_e32 v17, v17, v16
	v_cmp_eq_u32_e32 vcc, s93, v17
	s_cbranch_vccnz .LBB0_18
	s_and_b32 s2, s37, 0xff
	s_cmp_eq_u32 s2, 0
	s_mov_b64 s[2:3], -1
	s_mov_b64 s[38:39], -1
	s_cbranch_scc0 .LBB0_23
	v_readlane_b32 s2, v249, 8
	v_readlane_b32 s3, v249, 9
	s_nop 4
	global_load_dword v17, v1, s[2:3] sc1
	s_waitcnt vmcnt(0)
	v_cmp_eq_u32_e32 vcc, 0, v17
	s_cbranch_vccnz .LBB0_25
	s_mov_b64 s[38:39], 0
	s_mov_b64 s[2:3], -1

.LBB0_37:
	s_and_b32 s44, s37, 0xff
	s_mov_b64 s[42:43], -1
	s_cmp_lg_u32 s44, 0
	s_mov_b64 s[46:47], -1
	s_cbranch_scc1 .LBB0_40
	v_readlane_b32 s44, v249, 8
	v_readlane_b32 s45, v249, 9
	s_nop 4
	global_load_dword v2, v1, s[44:45] sc1
	s_waitcnt vmcnt(0)
	v_cmp_eq_u32_e32 vcc, 0, v2
	s_cbranch_vccnz .LBB0_42
	s_mov_b64 s[46:47], 0
	s_mov_b64 s[44:45], -1

.LBB0_1312:
	s_and_b32 s44, s37, 0xff
	s_mov_b64 s[42:43], -1
	s_cmp_lg_u32 s44, 0
	s_mov_b64 s[46:47], -1
	s_cbranch_scc1 .LBB0_1315
	v_readlane_b32 s30, v249, 8
	v_readlane_b32 s31, v249, 9
	s_nop 4
	global_load_dword v2, v1, s[30:31] sc1
	s_waitcnt vmcnt(0)
	v_cmp_eq_u32_e32 vcc, 0, v2
	s_cbranch_vccnz .LBB0_1317
	s_mov_b64 s[46:47], 0
	s_mov_b64 s[44:45], -1

.LBB0_1352:
	global_load_dword v2, v1, s[2:3] offset:32 sc1
	s_waitcnt vmcnt(0)
	v_and_b32_e32 v2, 0xffff0000, v2
	v_cmp_ne_u32_e32 vcc, v2, v0
	s_or_b64 s[28:29], vcc, s[28:29]
	s_andn2_b64 exec, exec, s[28:29]
	s_cbranch_execnz .LBB0_1352
	s_getpc_b64 s[98:99]
